# FoX row-sum trees split around the mid-chain MFMA: first-level packed adds before its LDS wait, the rest after (same math as the previous version)
# speedup vs baseline: 1.0033x; 1.0018x over previous
.LBB0_468:
	v_add_f32_e32 v171, 0xc2200000, v0
	s_add_i32 s18, s57, 0
	v_cmp_lt_f32_e32 vcc, v173, v171
	v_mov_b32_e32 v173, 0
	s_cmp_eq_u64 vcc, exec
	v_add3_u32 v169, s18, v159, v158
	s_cbranch_scc1 .LBB0_473
	v_pk_add_f32 v[84:85], v[84:85], v[0:1] op_sel_hi:[1,0] neg_lo:[0,1] neg_hi:[0,1]
	v_exp_f32_e32 v173, v84
	v_exp_f32_e32 v175, v85
	v_pk_add_f32 v[86:87], v[86:87], v[0:1] op_sel_hi:[1,0] neg_lo:[0,1] neg_hi:[0,1]
	v_exp_f32_e32 v179, v86
	v_exp_f32_e32 v181, v87
	v_pk_add_f32 v[88:89], v[88:89], v[0:1] op_sel_hi:[1,0] neg_lo:[0,1] neg_hi:[0,1]
	v_exp_f32_e32 v182, v88
	v_exp_f32_e32 v183, v89
	v_pk_add_f32 v[90:91], v[90:91], v[0:1] op_sel_hi:[1,0] neg_lo:[0,1] neg_hi:[0,1]
	v_exp_f32_e32 v184, v90
	v_exp_f32_e32 v185, v91
	v_pk_add_f32 v[92:93], v[92:93], v[0:1] op_sel_hi:[1,0] neg_lo:[0,1] neg_hi:[0,1]
	v_exp_f32_e32 v186, v92
	v_exp_f32_e32 v187, v93
	v_pk_add_f32 v[94:95], v[94:95], v[0:1] op_sel_hi:[1,0] neg_lo:[0,1] neg_hi:[0,1]
	v_exp_f32_e32 v188, v94
	v_exp_f32_e32 v189, v95
	ds_read_b64_tr_b16 v[84:85], v169 offset:36864
	ds_read_b64_tr_b16 v[86:87], v169 offset:38016
	v_pk_add_f32 v[96:97], v[96:97], v[0:1] op_sel_hi:[1,0] neg_lo:[0,1] neg_hi:[0,1]
	v_exp_f32_e32 v96, v96
	v_cvt_pk_bf16_f32 v88, v173, v175
	v_cvt_pk_bf16_f32 v89, v179, v181
	v_cvt_pk_bf16_f32 v90, v182, v183
	v_cvt_pk_bf16_f32 v91, v184, v185
	ds_read_b64_tr_b16 v[94:95], v169 offset:38080
	ds_read_b64_tr_b16 v[92:93], v169 offset:36928
	s_waitcnt lgkmcnt(2)
	v_mfma_f32_32x32x16_bf16 v[18:33], v[84:87], v[88:91], v[18:33]
	v_exp_f32_e32 v97, v97
	v_pk_add_f32 v[98:99], v[98:99], v[0:1] op_sel_hi:[1,0] neg_lo:[0,1] neg_hi:[0,1]
	v_exp_f32_e32 v98, v98
	ds_read_b64_tr_b16 v[84:85], v169 offset:39168
	ds_read_b64_tr_b16 v[86:87], v169 offset:40320
	v_exp_f32_e32 v99, v99
	s_waitcnt lgkmcnt(2)
	v_mfma_f32_32x32x16_bf16 v[2:17], v[92:95], v[88:91], v[2:17]
	v_cvt_pk_bf16_f32 v88, v186, v187
	v_cvt_pk_bf16_f32 v89, v188, v189
	v_cvt_pk_bf16_f32 v90, v96, v97
	v_cvt_pk_bf16_f32 v91, v98, v99
	ds_read_b64_tr_b16 v[94:95], v169 offset:40384
	ds_read_b64_tr_b16 v[92:93], v169 offset:39232
	s_waitcnt lgkmcnt(2)
	v_mfma_f32_32x32x16_bf16 v[18:33], v[84:87], v[88:91], v[18:33]
	v_pk_add_f32 v[84:85], v[182:183], v[184:185]
	v_pk_add_f32 v[186:187], v[186:187], v[188:189]
	v_pk_add_f32 v[96:97], v[96:97], v[98:99]
	v_add_f32_e32 v173, v175, v173
	v_add_f32_e32 v173, v179, v173
	v_add_f32_e32 v173, v181, v173
	s_waitcnt lgkmcnt(0)
	v_mfma_f32_32x32x16_bf16 v[2:17], v[92:95], v[88:91], v[2:17]
	v_pk_add_f32 v[84:85], v[84:85], v[186:187]
	v_pk_add_f32 v[84:85], v[84:85], v[96:97]
	v_add_f32_e32 v84, v84, v85
	v_add_f32_e32 v173, v84, v173
	v_cmp_lt_f32_e32 vcc, v174, v171
	s_cmp_eq_u64 vcc, exec
	s_cbranch_scc0 .LBB0_474

.LBB0_471:
	v_pk_add_f32 v[52:53], v[52:53], v[0:1] op_sel_hi:[1,0] neg_lo:[0,1] neg_hi:[0,1]
	v_exp_f32_e32 v68, v52
	v_exp_f32_e32 v69, v53
	v_pk_add_f32 v[54:55], v[54:55], v[0:1] op_sel_hi:[1,0] neg_lo:[0,1] neg_hi:[0,1]
	v_exp_f32_e32 v70, v54
	v_exp_f32_e32 v71, v55
	v_pk_add_f32 v[56:57], v[56:57], v[0:1] op_sel_hi:[1,0] neg_lo:[0,1] neg_hi:[0,1]
	v_exp_f32_e32 v72, v56
	v_exp_f32_e32 v73, v57
	v_pk_add_f32 v[58:59], v[58:59], v[0:1] op_sel_hi:[1,0] neg_lo:[0,1] neg_hi:[0,1]
	v_exp_f32_e32 v74, v58
	v_exp_f32_e32 v75, v59
	v_pk_add_f32 v[60:61], v[60:61], v[0:1] op_sel_hi:[1,0] neg_lo:[0,1] neg_hi:[0,1]
	v_exp_f32_e32 v76, v60
	v_exp_f32_e32 v77, v61
	v_pk_add_f32 v[62:63], v[62:63], v[0:1] op_sel_hi:[1,0] neg_lo:[0,1] neg_hi:[0,1]
	v_exp_f32_e32 v78, v62
	v_exp_f32_e32 v79, v63
	ds_read_b64_tr_b16 v[52:53], v169 offset:46080
	ds_read_b64_tr_b16 v[54:55], v169 offset:47232
	v_pk_add_f32 v[64:65], v[64:65], v[0:1] op_sel_hi:[1,0] neg_lo:[0,1] neg_hi:[0,1]
	v_exp_f32_e32 v64, v64
	v_cvt_pk_bf16_f32 v56, v68, v69
	v_cvt_pk_bf16_f32 v57, v70, v71
	v_cvt_pk_bf16_f32 v58, v72, v73
	v_cvt_pk_bf16_f32 v59, v74, v75
	ds_read_b64_tr_b16 v[62:63], v169 offset:47296
	ds_read_b64_tr_b16 v[60:61], v169 offset:46144
	s_waitcnt lgkmcnt(2)
	v_mfma_f32_32x32x16_bf16 v[18:33], v[52:55], v[56:59], v[18:33]
	v_exp_f32_e32 v65, v65
	v_pk_add_f32 v[66:67], v[66:67], v[0:1] op_sel_hi:[1,0] neg_lo:[0,1] neg_hi:[0,1]
	v_exp_f32_e32 v66, v66
	ds_read_b64_tr_b16 v[52:53], v169 offset:48384
	ds_read_b64_tr_b16 v[54:55], v169 offset:49536
	v_exp_f32_e32 v67, v67
	s_waitcnt lgkmcnt(2)
	v_mfma_f32_32x32x16_bf16 v[2:17], v[60:63], v[56:59], v[2:17]
	v_cvt_pk_bf16_f32 v56, v76, v77
	v_cvt_pk_bf16_f32 v57, v78, v79
	v_cvt_pk_bf16_f32 v58, v64, v65
	v_cvt_pk_bf16_f32 v59, v66, v67
	ds_read_b64_tr_b16 v[62:63], v169 offset:49600
	ds_read_b64_tr_b16 v[60:61], v169 offset:48448
	s_waitcnt lgkmcnt(2)
	v_mfma_f32_32x32x16_bf16 v[18:33], v[52:55], v[56:59], v[18:33]
	v_pk_add_f32 v[52:53], v[68:69], v[70:71]
	v_pk_add_f32 v[72:73], v[72:73], v[74:75]
	v_pk_add_f32 v[76:77], v[76:77], v[78:79]
	v_pk_add_f32 v[64:65], v[64:65], v[66:67]
	s_waitcnt lgkmcnt(0)
	v_mfma_f32_32x32x16_bf16 v[2:17], v[60:63], v[56:59], v[2:17]
	v_pk_add_f32 v[52:53], v[52:53], v[72:73]
	v_pk_add_f32 v[76:77], v[76:77], v[64:65]
	v_pk_add_f32 v[52:53], v[52:53], v[76:77]
	v_add_f32_e32 v52, v52, v53
	v_add_f32_e32 v173, v52, v173
	v_cmp_lt_f32_e32 vcc, v170, v171
	s_cmp_eq_u64 vcc, exec
	s_cbranch_scc0 .LBB0_476
	s_branch .LBB0_477

.LBB0_474:
	v_pk_add_f32 v[68:69], v[68:69], v[0:1] op_sel_hi:[1,0] neg_lo:[0,1] neg_hi:[0,1]
	v_exp_f32_e32 v84, v68
	v_exp_f32_e32 v85, v69
	v_pk_add_f32 v[70:71], v[70:71], v[0:1] op_sel_hi:[1,0] neg_lo:[0,1] neg_hi:[0,1]
	v_exp_f32_e32 v86, v70
	v_exp_f32_e32 v87, v71
	v_pk_add_f32 v[72:73], v[72:73], v[0:1] op_sel_hi:[1,0] neg_lo:[0,1] neg_hi:[0,1]
	v_exp_f32_e32 v88, v72
	v_exp_f32_e32 v89, v73
	v_pk_add_f32 v[74:75], v[74:75], v[0:1] op_sel_hi:[1,0] neg_lo:[0,1] neg_hi:[0,1]
	v_exp_f32_e32 v90, v74
	v_exp_f32_e32 v91, v75
	v_pk_add_f32 v[76:77], v[76:77], v[0:1] op_sel_hi:[1,0] neg_lo:[0,1] neg_hi:[0,1]
	v_exp_f32_e32 v92, v76
	v_exp_f32_e32 v93, v77
	v_pk_add_f32 v[78:79], v[78:79], v[0:1] op_sel_hi:[1,0] neg_lo:[0,1] neg_hi:[0,1]
	v_exp_f32_e32 v94, v78
	v_exp_f32_e32 v95, v79
	ds_read_b64_tr_b16 v[68:69], v169 offset:41472
	ds_read_b64_tr_b16 v[70:71], v169 offset:42624
	v_pk_add_f32 v[80:81], v[80:81], v[0:1] op_sel_hi:[1,0] neg_lo:[0,1] neg_hi:[0,1]
	v_exp_f32_e32 v80, v80
	v_cvt_pk_bf16_f32 v72, v84, v85
	v_cvt_pk_bf16_f32 v73, v86, v87
	v_cvt_pk_bf16_f32 v74, v88, v89
	v_cvt_pk_bf16_f32 v75, v90, v91
	ds_read_b64_tr_b16 v[78:79], v169 offset:42688
	ds_read_b64_tr_b16 v[76:77], v169 offset:41536
	s_waitcnt lgkmcnt(2)
	v_mfma_f32_32x32x16_bf16 v[18:33], v[68:71], v[72:75], v[18:33]
	v_exp_f32_e32 v81, v81
	v_pk_add_f32 v[82:83], v[82:83], v[0:1] op_sel_hi:[1,0] neg_lo:[0,1] neg_hi:[0,1]
	v_exp_f32_e32 v82, v82
	ds_read_b64_tr_b16 v[68:69], v169 offset:43776
	ds_read_b64_tr_b16 v[70:71], v169 offset:44928
	v_exp_f32_e32 v83, v83
	s_waitcnt lgkmcnt(2)
	v_mfma_f32_32x32x16_bf16 v[2:17], v[76:79], v[72:75], v[2:17]
	v_cvt_pk_bf16_f32 v72, v92, v93
	v_cvt_pk_bf16_f32 v73, v94, v95
	v_cvt_pk_bf16_f32 v74, v80, v81
	v_cvt_pk_bf16_f32 v75, v82, v83
	ds_read_b64_tr_b16 v[78:79], v169 offset:44992
	ds_read_b64_tr_b16 v[76:77], v169 offset:43840
	s_waitcnt lgkmcnt(2)
	v_mfma_f32_32x32x16_bf16 v[18:33], v[68:71], v[72:75], v[18:33]
	v_pk_add_f32 v[68:69], v[84:85], v[86:87]
	v_pk_add_f32 v[88:89], v[88:89], v[90:91]
	v_pk_add_f32 v[92:93], v[92:93], v[94:95]
	v_pk_add_f32 v[80:81], v[80:81], v[82:83]
	s_waitcnt lgkmcnt(0)
	v_mfma_f32_32x32x16_bf16 v[2:17], v[76:79], v[72:75], v[2:17]
	v_pk_add_f32 v[68:69], v[68:69], v[88:89]
	v_pk_add_f32 v[92:93], v[92:93], v[80:81]
	v_pk_add_f32 v[68:69], v[68:69], v[92:93]
	v_add_f32_e32 v68, v68, v69
	v_add_f32_e32 v173, v68, v173
	v_cmp_lt_f32_e32 vcc, v172, v171
	s_cmp_eq_u64 vcc, exec
	s_cbranch_scc0 .LBB0_471

.LBB0_476:
	v_pk_add_f32 v[36:37], v[36:37], v[0:1] op_sel_hi:[1,0] neg_lo:[0,1] neg_hi:[0,1]
	v_exp_f32_e32 v52, v36
	v_exp_f32_e32 v53, v37
	v_pk_add_f32 v[38:39], v[38:39], v[0:1] op_sel_hi:[1,0] neg_lo:[0,1] neg_hi:[0,1]
	v_exp_f32_e32 v54, v38
	v_exp_f32_e32 v55, v39
	v_pk_add_f32 v[40:41], v[40:41], v[0:1] op_sel_hi:[1,0] neg_lo:[0,1] neg_hi:[0,1]
	v_exp_f32_e32 v56, v40
	v_exp_f32_e32 v57, v41
	v_pk_add_f32 v[42:43], v[42:43], v[0:1] op_sel_hi:[1,0] neg_lo:[0,1] neg_hi:[0,1]
	v_exp_f32_e32 v58, v42
	v_exp_f32_e32 v59, v43
	v_pk_add_f32 v[44:45], v[44:45], v[0:1] op_sel_hi:[1,0] neg_lo:[0,1] neg_hi:[0,1]
	v_exp_f32_e32 v60, v44
	v_exp_f32_e32 v61, v45
	v_pk_add_f32 v[46:47], v[46:47], v[0:1] op_sel_hi:[1,0] neg_lo:[0,1] neg_hi:[0,1]
	v_exp_f32_e32 v62, v46
	v_exp_f32_e32 v63, v47
	ds_read_b64_tr_b16 v[36:37], v169 offset:50688
	ds_read_b64_tr_b16 v[38:39], v169 offset:51840
	v_pk_add_f32 v[48:49], v[48:49], v[0:1] op_sel_hi:[1,0] neg_lo:[0,1] neg_hi:[0,1]
	v_exp_f32_e32 v48, v48
	v_cvt_pk_bf16_f32 v40, v52, v53
	v_cvt_pk_bf16_f32 v41, v54, v55
	v_cvt_pk_bf16_f32 v42, v56, v57
	v_cvt_pk_bf16_f32 v43, v58, v59
	ds_read_b64_tr_b16 v[46:47], v169 offset:51904
	ds_read_b64_tr_b16 v[44:45], v169 offset:50752
	s_waitcnt lgkmcnt(2)
	v_mfma_f32_32x32x16_bf16 v[18:33], v[36:39], v[40:43], v[18:33]
	v_exp_f32_e32 v49, v49
	v_pk_add_f32 v[50:51], v[50:51], v[0:1] op_sel_hi:[1,0] neg_lo:[0,1] neg_hi:[0,1]
	v_exp_f32_e32 v50, v50
	ds_read_b64_tr_b16 v[36:37], v169 offset:52992
	ds_read_b64_tr_b16 v[38:39], v169 offset:54144
	v_exp_f32_e32 v51, v51
	s_waitcnt lgkmcnt(2)
	v_mfma_f32_32x32x16_bf16 v[2:17], v[44:47], v[40:43], v[2:17]
	v_cvt_pk_bf16_f32 v40, v60, v61
	v_cvt_pk_bf16_f32 v41, v62, v63
	v_cvt_pk_bf16_f32 v42, v48, v49
	v_cvt_pk_bf16_f32 v43, v50, v51
	ds_read_b64_tr_b16 v[46:47], v169 offset:54208
	ds_read_b64_tr_b16 v[44:45], v169 offset:53056
	s_waitcnt lgkmcnt(2)
	v_mfma_f32_32x32x16_bf16 v[18:33], v[36:39], v[40:43], v[18:33]
	v_pk_add_f32 v[36:37], v[52:53], v[54:55]
	v_pk_add_f32 v[56:57], v[56:57], v[58:59]
	v_pk_add_f32 v[60:61], v[60:61], v[62:63]
	v_pk_add_f32 v[48:49], v[48:49], v[50:51]
	s_waitcnt lgkmcnt(0)
	v_mfma_f32_32x32x16_bf16 v[2:17], v[44:47], v[40:43], v[2:17]
	v_pk_add_f32 v[36:37], v[36:37], v[56:57]
	v_pk_add_f32 v[60:61], v[60:61], v[48:49]
	v_pk_add_f32 v[36:37], v[36:37], v[60:61]
	v_add_f32_e32 v36, v36, v37
	v_add_f32_e32 v173, v36, v173
